# B2: loads of the fourth unrolled step stay in flight across the loop latch (counted waits, their Q values moved into the rotation one iteration later)
# baseline (speedup 1.0000x reference)
; __device__ __forceinline__ void rwkv_phase_b2(const Ctx& C) {
;     ...
;     for (int item = C.bid; item < 32; item += C.G) {
;         const int h = item >> 2, rb = item & 3;
;         for (int e = tid; e < 1024; e += NTHR) MAT(0)[(e >> 6) * MS + (e & 63)] = 0.f;
;         float pv[4][16], qv[4][4];
;         const size_t ob = (size_t)(h * NGRP) * 4096;
;         const int poff = (4 * q) * 64 + w * 16 + l15, qoff = (rb * 16 + 4 * q) * 64 + w * 16 + l15;
;         if (w < 4) {
; #pragma unroll
;             for (int s = 0; s < 4; ++s) {
; #pragma unroll
;                 for (int i = 0; i < 16; ++i) pv[s][i] = Pc[ob + (size_t)s * 4096 + poff + ((i & 3) + 16 * (i >> 2)) * 64];
; #pragma unroll
;                 for (int j = 0; j < 4; ++j) qv[s][j] = Qc[ob + (size_t)s * 4096 + qoff + j * 64];
;             }
;         }
;         __syncthreads();
;         for (int g0 = 0; g0 < NGRP; g0 += 4) {
; #pragma unroll
;             for (int s = 0; s < 4; ++s) {
;                 const int g = g0 + s; const size_t o = ob + (size_t)g * 4096;
;                 for (int e = tid; e < 1024; e += NTHR) Sg[o + (rb * 16 + (e >> 6)) * 64 + (e & 63)] = MAT(0)[(e >> 6) * MS + (e & 63)];
.LBB0_967:
	s_and_b32 s36, s1, 0xffffffe0
	s_lshl_b32 s35, s3, 8
	s_ashr_i32 s37, s36, 31
	s_and_b32 s35, s35, 0x3000
	s_lshl_b64 s[36:37], s[36:37], 14
	v_lshl_or_b32 v2, v37, 2, s35
	v_or_b32_e32 v2, s36, v2
	v_mov_b32_e32 v3, s37
	s_lshl_b64 s[22:23], s[22:23], 12
	v_lshl_add_u64 v[24:25], v[22:23], 0, v[2:3]
	v_lshl_add_u64 v[26:27], v[20:21], 0, v[2:3]
	v_lshl_add_u64 v[28:29], v[18:19], 0, v[2:3]
	v_lshl_add_u64 v[30:31], v[16:17], 0, v[2:3]
	s_mov_b32 s35, 0
	s_waitcnt vmcnt(0)
	v_mov_b32_e32 v113, v132
	v_mov_b32_e32 v114, v130
	v_mov_b32_e32 v115, v129
	v_mov_b32_e32 v116, v131
	v_mov_b32_e32 v121, v120
	v_mov_b32_e32 v122, v119
	v_mov_b32_e32 v123, v117
	v_mov_b32_e32 v124, v118
	v_mov_b32_e32 v163, v132
	v_mov_b32_e32 v161, v130
	v_mov_b32_e32 v160, v129
	v_mov_b32_e32 v162, v131
	v_mov_b32_e32 v129, v112
	v_mov_b32_e32 v130, v111
	v_mov_b32_e32 v131, v110
	v_mov_b32_e32 v132, v109
	v_mov_b32_e32 v117, v108
	v_mov_b32_e32 v118, v106
	v_mov_b32_e32 v119, v105
	v_mov_b32_e32 v120, v107
	s_waitcnt lgkmcnt(0)
	s_barrier
	ds_read_b32 v142, v36
	ds_read_b32 v143, v36 offset:2176
	v_lshrrev_b32_e32 v150, 4, v193
	v_mul_u32_u24_e32 v150, 0x3c0, v150
	s_mul_i32 s56, s80, 0xc0
	v_subrev_u32_e32 v150, s56, v150
	v_ashrrev_i32_e32 v151, 31, v150
	s_waitcnt lgkmcnt(0)
	global_store_dword v[30:31], v142, off
	global_store_dword v[30:31], v143, off offset:2048

; #define LAS __attribute__((address_space(3)))
; __device__ __forceinline__ void rwkv_phase_b2(const Ctx& C) {
;     ...
;                 f32x4 a0 = (f32x4){0.f, 0.f, 0.f, 0.f}, a1 = a0; float qc[4];
;                 if (w < 4) {
;                     const LAS float* m0 = MAT(0);
; #pragma unroll
;                     for (int kb = 0; kb < 4; kb += 2) {
;                         const f32x4 s0 = *(const LAS f32x4*)(m0 + l15 * MS + 16 * kb + 4 * q), s1 = *(const LAS f32x4*)(m0 + l15 * MS + 16 * (kb + 1) + 4 * q);
; #pragma unroll
;                         for (int j = 0; j < 4; ++j) {
;                             a0 = __builtin_amdgcn_mfma_f32_16x16x4f32(s0[j], pv[s][4 * kb + j], a0, 0, 0, 0);
;                             a1 = __builtin_amdgcn_mfma_f32_16x16x4f32(s1[j], pv[s][4 * (kb + 1) + j], a1, 0, 0, 0);
;                         }
;                     }
; #pragma unroll
;                     for (int j = 0; j < 4; ++j) qc[j] = qv[s][j];
;                     if (g + 4 < NGRP) {
; #pragma unroll
;                         for (int i = 0; i < 16; ++i) pv[s][i] = Pc[o + 4 * 4096 + poff + ((i & 3) + 16 * (i >> 2)) * 64];
; #pragma unroll
;                         for (int j = 0; j < 4; ++j) qv[s][j] = Qc[o + 4 * 4096 + qoff + j * 64];
;                     }
.LBB0_992:
	s_nop 3
	s_waitcnt lgkmcnt(0)
	s_barrier
	s_and_b64 vcc, exec, s[6:7]
	v_mov_b32_e32 v2, 0
	s_cbranch_vccnz .LBB0_998
	s_waitcnt vmcnt(16)
	v_mov_b32_e32 v113, v163
	v_mov_b32_e32 v114, v161
	v_mov_b32_e32 v115, v160
	v_mov_b32_e32 v116, v162
	ds_read_b128 v[2:5], v35
	ds_read_b128 v[6:9], v35 offset:64
	s_cmp_gt_u32 s35, 27
	s_waitcnt lgkmcnt(1)
	v_mfma_f32_16x16x4_f32 v[122:125], v2, v89, 0
	s_waitcnt lgkmcnt(0)
	v_mfma_f32_16x16x4_f32 v[126:129], v6, v93, 0
	v_mfma_f32_16x16x4_f32 v[122:125], v3, v79, v[122:125]
	v_mfma_f32_16x16x4_f32 v[126:129], v7, v90, v[126:129]
	v_mfma_f32_16x16x4_f32 v[122:125], v4, v80, v[122:125]
	v_mfma_f32_16x16x4_f32 v[126:129], v8, v91, v[126:129]
	v_mfma_f32_16x16x4_f32 v[2:5], v5, v81, v[122:125]
	s_nop 7
	ds_read_b128 v[122:125], v35 offset:128
	ds_read_b128 v[130:133], v35 offset:192
	v_mfma_f32_16x16x4_f32 v[6:9], v9, v97, v[126:129]
	v_mov_b32_e32 v129, v115
	s_waitcnt lgkmcnt(1)
	v_mfma_f32_16x16x4_f32 v[2:5], v122, v96, v[2:5]
	s_waitcnt lgkmcnt(0)
	v_mfma_f32_16x16x4_f32 v[6:9], v130, v82, v[6:9]
	v_mov_b32_e32 v130, v114
	v_mfma_f32_16x16x4_f32 v[2:5], v123, v86, v[2:5]
	v_mfma_f32_16x16x4_f32 v[6:9], v131, v83, v[6:9]
	v_mov_b32_e32 v131, v116
	v_mfma_f32_16x16x4_f32 v[2:5], v124, v87, v[2:5]
	v_mfma_f32_16x16x4_f32 v[6:9], v132, v84, v[6:9]
	v_mov_b32_e32 v132, v113
	v_mfma_f32_16x16x4_f32 v[2:5], v125, v88, v[2:5]
	v_mfma_f32_16x16x4_f32 v[6:9], v133, v85, v[6:9]
	s_cbranch_scc1 .LBB0_997
	s_or_b32 s36, s36, 0x3000
	s_add_u32 s36, s22, s36
	s_addc_u32 s37, s23, 0
	s_lshl_b64 s[36:37], s[36:37], 2
	s_add_u32 s38, s10, s36
	s_addc_u32 s39, s11, s37
	v_lshl_add_u64 v[80:81], v[10:11], 2, s[38:39]
	v_add_co_u32_e32 v96, vcc, s30, v80
	s_add_u32 s36, s12, s36
	s_nop 0
	v_addc_co_u32_e32 v97, vcc, 0, v81, vcc
	v_add_co_u32_e32 v88, vcc, s31, v80
	s_addc_u32 s37, s13, s37
	s_nop 0
	v_addc_co_u32_e32 v89, vcc, 0, v81, vcc
	v_add_co_u32_e32 v122, vcc, s33, v80
	v_lshl_add_u64 v[86:87], v[80:81], 0, s[20:21]
	s_nop 0
	v_addc_co_u32_e32 v123, vcc, 0, v81, vcc
	v_lshl_add_u64 v[80:81], v[12:13], 2, s[36:37]
	v_add_co_u32_e32 v126, vcc, 0x10000, v80
	global_load_dword v82, v[122:123], off
	global_load_dword v83, v[122:123], off offset:256
	global_load_dword v84, v[122:123], off offset:512
	global_load_dword v85, v[122:123], off offset:768
	v_lshl_add_u64 v[124:125], v[80:81], 0, s[20:21]
	v_addc_co_u32_e32 v127, vcc, 0, v81, vcc
	global_load_dword v79, v[86:87], off offset:256
	global_load_dword v80, v[86:87], off offset:512
	global_load_dword v81, v[86:87], off offset:768
	s_nop 0
	global_load_dword v86, v[88:89], off offset:256
	global_load_dword v87, v[88:89], off offset:512
	s_nop 0
	global_load_dword v88, v[88:89], off offset:768
	s_nop 0
	global_load_dword v160, v[124:125], off offset:256
	global_load_dword v161, v[124:125], off offset:512
	global_load_dword v89, v[96:97], off offset:-4096
	global_load_dword v93, v[96:97], off
	global_load_dword v90, v[96:97], off offset:256
	global_load_dword v91, v[96:97], off offset:512
	s_nop 0
	global_load_dword v97, v[96:97], off offset:768
	s_nop 0
	global_load_dword v96, v[122:123], off offset:-4096
	global_load_dword v162, v[126:127], off
	global_load_dword v163, v[124:125], off offset:768

; __device__ __forceinline__ void rwkv_phase_b2(const Ctx& C) {
;     ...
; #pragma unroll
;                     for (int j = 0; j < 4; ++j) qc[j] = qv[s][j];
;                     if (g + 4 < NGRP) {
; #pragma unroll
;                         for (int i = 0; i < 16; ++i) pv[s][i] = Pc[o + 4 * 4096 + poff + ((i & 3) + 16 * (i >> 2)) * 64];
; #pragma unroll
;                         for (int j = 0; j < 4; ++j) qv[s][j] = Qc[o + 4 * 4096 + qoff + j * 64];
;                     }
.Lmy_b2_nostore:
.LBB0_1001:
	s_add_i32 s36, s35, 4
	v_lshl_add_u64 v[30:31], v[30:31], 0, s[20:21]
	v_lshl_add_u64 v[28:29], v[28:29], 0, s[20:21]
	v_lshl_add_u64 v[26:27], v[26:27], 0, s[20:21]
	s_cmp_gt_u32 s35, 27
	v_lshl_add_u64 v[24:25], v[24:25], 0, s[20:21]
	s_waitcnt lgkmcnt(0)
	s_barrier
	s_cbranch_scc1 .LBB0_958
	s_waitcnt vmcnt(24)
	v_mov_b32_e32 v121, v120
	v_mov_b32_e32 v122, v119
	v_mov_b32_e32 v123, v117
	v_mov_b32_e32 v124, v118
	v_mov_b32_e32 v129, v112
	v_mov_b32_e32 v130, v111
	v_mov_b32_e32 v131, v110
	v_mov_b32_e32 v132, v109
	v_mov_b32_e32 v117, v108
	v_mov_b32_e32 v118, v106
	v_mov_b32_e32 v119, v105
	v_mov_b32_e32 v120, v107
	s_mov_b32 s35, s36
	s_branch .LBB0_968
